# v28 + one static s_setprio 1 for waves 0-3 at kernel entry (mirror of the previous half)
# speedup vs baseline: 1.0077x; 1.0077x over previous
_Z14fwd_megakernel6Params:
	s_load_dwordx8 s[88:95], s[0:1], 0x180
	s_mov_b32 s96, s2
	v_readfirstlane_b32 s98, v0
	s_nop 3
	s_and_b32 s98, s98, 0x3ff
	s_lshr_b32 s98, s98, 6
	s_cmp_lt_u32 s98, 4
	s_cbranch_scc0 .Lprio_done
	s_setprio 1
